# conversion split plus nt KV-cache stream plus loader keeping two tiles in flight (counted waits)
# baseline (speedup 1.0000x reference)
.LBB0_825:
	s_waitcnt vmcnt(31)
	v_mul_f32_e32 v135, 0x41800000, v68
	v_mul_f32_e32 v136, 0x41800000, v69
	v_mov_b32_e32 v140, 0
	v_cvt_pk_fp8_f32 v140, v135, v136
	s_add_i32 s13, s12, 1
	s_cmp_lg_u32 s12, 2
	v_mul_f32_e32 v137, 0x41800000, v70
	v_mul_f32_e32 v139, 0x41800000, v71
	s_cselect_b32 s12, s13, 0
	v_cvt_pk_fp8_f32 v140, v137, v139 op_sel:[0,0,1]
	s_mul_i32 s13, s12, 0x4c00
	s_add_i32 s13, s13, 0
	v_add_u32_e32 v134, s13, v1
	s_waitcnt lgkmcnt(0)
	s_barrier
	ds_write_b32 v134, v140
	s_waitcnt vmcnt(30)
	v_mul_f32_e32 v135, 0x41800000, v72
	v_mul_f32_e32 v136, 0x41800000, v73
	v_mov_b32_e32 v140, 0
	v_cvt_pk_fp8_f32 v140, v135, v136
	v_mul_f32_e32 v137, 0x41800000, v74
	v_mul_f32_e32 v139, 0x41800000, v75
	s_waitcnt vmcnt(29)
	v_mul_f32_e32 v135, 0x41800000, v76
	v_cvt_pk_fp8_f32 v140, v137, v139 op_sel:[0,0,1]
	v_mul_f32_e32 v136, 0x41800000, v77
	v_mul_f32_e32 v137, 0x41800000, v78
	v_mul_f32_e32 v139, 0x41800000, v79
	ds_write_b32 v134, v140 offset:1152
	v_mov_b32_e32 v140, 0
	v_cvt_pk_fp8_f32 v140, v135, v136
	s_waitcnt vmcnt(28)
	v_mul_f32_e32 v135, 0x41800000, v80
	v_mul_f32_e32 v136, 0x41800000, v81
	v_mov_b32_e32 v141, 0
	v_cvt_pk_fp8_f32 v140, v137, v139 op_sel:[0,0,1]
	v_mul_f32_e32 v137, 0x41800000, v82
	v_mul_f32_e32 v139, 0x41800000, v83
	v_mov_b32_e32 v142, 0
	ds_write_b32 v134, v140 offset:2304
	v_mov_b32_e32 v140, 0
	v_cvt_pk_fp8_f32 v140, v135, v136
	s_waitcnt vmcnt(27)
	v_mul_f32_e32 v135, 0x41800000, v84
	v_mul_f32_e32 v136, 0x41800000, v85
	v_mov_b32_e32 v143, 0
	v_cvt_pk_fp8_f32 v140, v137, v139 op_sel:[0,0,1]
	v_mul_f32_e32 v137, 0x41800000, v86
	v_mul_f32_e32 v139, 0x41800000, v87
	v_mov_b32_e32 v144, 0
	ds_write_b32 v134, v140 offset:3456
	v_mov_b32_e32 v140, 0
	v_cvt_pk_fp8_f32 v140, v135, v136
	s_waitcnt vmcnt(26)
	v_mul_f32_e32 v135, 0x41800000, v88
	v_mul_f32_e32 v136, 0x41800000, v89
	s_cmp_gt_u32 s9, 29
	v_cvt_pk_fp8_f32 v140, v137, v139 op_sel:[0,0,1]
	v_mul_f32_e32 v137, 0x41800000, v90
	v_mul_f32_e32 v139, 0x41800000, v91
	ds_write_b32 v134, v140 offset:4608
	v_mov_b32_e32 v140, 0
	v_cvt_pk_fp8_f32 v140, v135, v136
	s_waitcnt vmcnt(25)
	v_mul_f32_e32 v135, 0x41800000, v92
	v_mul_f32_e32 v136, 0x41800000, v93
	v_cvt_pk_fp8_f32 v140, v137, v139 op_sel:[0,0,1]
	v_mul_f32_e32 v137, 0x41800000, v94
	v_mul_f32_e32 v139, 0x41800000, v95
	ds_write_b32 v134, v140 offset:5760
	v_mov_b32_e32 v140, 0
	v_cvt_pk_fp8_f32 v140, v135, v136
	s_waitcnt vmcnt(24)
	v_mul_f32_e32 v135, 0x41800000, v96
	v_mul_f32_e32 v136, 0x41800000, v97
	v_cvt_pk_fp8_f32 v140, v137, v139 op_sel:[0,0,1]
	v_mul_f32_e32 v137, 0x41800000, v98
	v_mul_f32_e32 v139, 0x41800000, v99
	ds_write_b32 v134, v140 offset:6912
	v_mov_b32_e32 v140, 0
	v_cvt_pk_fp8_f32 v140, v135, v136
	s_waitcnt vmcnt(23)
	v_mul_f32_e32 v135, 0x41800000, v100
	s_waitcnt vmcnt(22)
	v_mul_f32_e32 v136, 0x41800000, v104
	v_cvt_pk_fp8_f32 v140, v137, v139 op_sel:[0,0,1]
	s_waitcnt vmcnt(21)
	v_mul_f32_e32 v137, 0x41800000, v108
	s_waitcnt vmcnt(20)
	v_mul_f32_e32 v139, 0x41800000, v112
	ds_write_b32 v134, v140 offset:8064
	v_mov_b32_e32 v140, 0
	v_cvt_pk_fp8_f32 v140, v135, v136
	v_mul_f32_e32 v135, 0x41800000, v101
	v_mul_f32_e32 v136, 0x41800000, v105
	v_cvt_pk_fp8_f32 v141, v135, v136
	v_mul_f32_e32 v135, 0x41800000, v102
	v_mul_f32_e32 v136, 0x41800000, v106
	v_cvt_pk_fp8_f32 v142, v135, v136
	v_mul_f32_e32 v135, 0x41800000, v103
	v_mul_f32_e32 v136, 0x41800000, v107
	v_cvt_pk_fp8_f32 v143, v135, v136
	s_waitcnt vmcnt(19)
	v_mul_f32_e32 v135, 0x41800000, v116
	s_waitcnt vmcnt(18)
	v_mul_f32_e32 v136, 0x41800000, v120
	v_cvt_pk_fp8_f32 v140, v137, v139 op_sel:[0,0,1]
	v_mul_f32_e32 v137, 0x41800000, v109
	v_mul_f32_e32 v139, 0x41800000, v113
	v_cvt_pk_fp8_f32 v144, v135, v136
	v_cvt_pk_fp8_f32 v141, v137, v139 op_sel:[0,0,1]
	v_mul_f32_e32 v137, 0x41800000, v110
	v_mul_f32_e32 v139, 0x41800000, v114
	v_cvt_pk_fp8_f32 v142, v137, v139 op_sel:[0,0,1]
	v_mul_f32_e32 v137, 0x41800000, v111
	v_mul_f32_e32 v139, 0x41800000, v115
	v_cvt_pk_fp8_f32 v143, v137, v139 op_sel:[0,0,1]
	s_waitcnt vmcnt(17)
	v_mul_f32_e32 v137, 0x41800000, v124
	s_waitcnt vmcnt(16)
	v_mul_f32_e32 v139, 0x41800000, v128
	v_cvt_pk_fp8_f32 v144, v137, v139 op_sel:[0,0,1]
	v_add_u32_e32 v134, s13, v138
	v_add_u32_e32 v134, 0x2400, v134
	v_mul_f32_e32 v135, 0x41800000, v117
	ds_write2_b32 v134, v140, v144 offset1:8
	v_mul_f32_e32 v136, 0x41800000, v121
	v_mov_b32_e32 v140, 0
	v_cvt_pk_fp8_f32 v140, v135, v136
	v_mul_f32_e32 v137, 0x41800000, v125
	v_mul_f32_e32 v139, 0x41800000, v129
	v_mul_f32_e32 v135, 0x41800000, v118
	v_cvt_pk_fp8_f32 v140, v137, v139 op_sel:[0,0,1]
	v_mul_f32_e32 v136, 0x41800000, v122
	v_mul_f32_e32 v137, 0x41800000, v126
	v_mul_f32_e32 v139, 0x41800000, v130
	ds_write2_b32 v134, v141, v140 offset0:20 offset1:28
	v_mov_b32_e32 v140, 0
	v_cvt_pk_fp8_f32 v140, v135, v136
	v_mul_f32_e32 v135, 0x41800000, v119
	v_mul_f32_e32 v136, 0x41800000, v123
	v_cvt_pk_fp8_f32 v140, v137, v139 op_sel:[0,0,1]
	v_mul_f32_e32 v137, 0x41800000, v127
	v_mul_f32_e32 v139, 0x41800000, v131
	ds_write2_b32 v134, v142, v140 offset0:40 offset1:48
	v_mov_b32_e32 v140, 0
	v_cvt_pk_fp8_f32 v140, v135, v136
	v_cvt_pk_fp8_f32 v140, v137, v139 op_sel:[0,0,1]
	ds_write2_b32 v134, v143, v140 offset0:60 offset1:68
	s_cbranch_scc1 .LBB0_822
	s_add_u32 s13, s0, s95
	s_addc_u32 s14, s1, 0
	s_add_u32 s13, s13, 0x140000
	s_addc_u32 s14, s14, 0
	s_add_u32 s15, s2, s95
	s_addc_u32 s23, s8, 0
	s_add_u32 s34, s15, 0x140000
	s_addc_u32 s23, s23, 0
	s_cmp_lt_u32 s9, 28
	s_cselect_b32 s15, s14, s25
	s_cselect_b32 s14, s13, s3
	v_lshl_add_u64 v[92:93], s[14:15], 0, v[2:3]
	v_add_co_u32_e32 v72, vcc, s90, v92
	s_cselect_b32 s15, s23, s51
	s_nop 0
	v_addc_co_u32_e32 v73, vcc, 0, v93, vcc
	v_add_co_u32_e32 v76, vcc, s37, v92
	s_cselect_b32 s14, s34, s39
	s_nop 0
	v_addc_co_u32_e32 v77, vcc, 0, v93, vcc
	v_add_co_u32_e32 v80, vcc, s38, v92
	v_lshl_add_u64 v[124:125], s[14:15], 0, v[132:133]
	s_nop 0
	v_addc_co_u32_e32 v81, vcc, 0, v93, vcc
	v_add_co_u32_e32 v84, vcc, s53, v92
	global_load_dwordx4 v[68:71], v[92:93], off nt
	s_nop 0
	global_load_dwordx4 v[72:75], v[72:73], off nt
	v_addc_co_u32_e32 v85, vcc, 0, v93, vcc
	v_add_co_u32_e32 v88, vcc, s55, v92
	global_load_dwordx4 v[76:79], v[76:77], off nt
	s_nop 0
	global_load_dwordx4 v[80:83], v[80:81], off nt
	v_addc_co_u32_e32 v89, vcc, 0, v93, vcc
	v_add_co_u32_e32 v94, vcc, s91, v92
	global_load_dwordx4 v[84:87], v[84:85], off nt
	s_nop 0
	global_load_dwordx4 v[88:91], v[88:89], off nt
	v_addc_co_u32_e32 v95, vcc, 0, v93, vcc
	v_add_co_u32_e32 v96, vcc, s93, v92
	s_nop 1
	v_addc_co_u32_e32 v97, vcc, 0, v93, vcc
	v_add_co_u32_e32 v104, vcc, s27, v124
	global_load_dwordx4 v[92:95], v[94:95], off nt
	s_nop 0
	global_load_dwordx4 v[96:99], v[96:97], off nt
	v_addc_co_u32_e32 v105, vcc, 0, v125, vcc
	v_add_co_u32_e32 v108, vcc, 0x2000, v124
	global_load_dwordx4 v[100:103], v[124:125], off nt
	s_nop 0
	global_load_dwordx4 v[104:107], v[104:105], off nt
	v_addc_co_u32_e32 v109, vcc, 0, v125, vcc
	v_add_co_u32_e32 v112, vcc, 0x3000, v124
	s_nop 1
	v_addc_co_u32_e32 v113, vcc, 0, v125, vcc
	v_add_co_u32_e32 v116, vcc, 0x4000, v124
	global_load_dwordx4 v[108:111], v[108:109], off nt
	s_nop 0
	global_load_dwordx4 v[112:115], v[112:113], off nt
	v_addc_co_u32_e32 v117, vcc, 0, v125, vcc
	v_add_co_u32_e32 v120, vcc, 0x5000, v124
	s_nop 1
	v_addc_co_u32_e32 v121, vcc, 0, v125, vcc
	v_add_co_u32_e32 v126, vcc, 0x6000, v124
	global_load_dwordx4 v[116:119], v[116:117], off nt
	s_nop 0
	global_load_dwordx4 v[120:123], v[120:121], off nt
	v_addc_co_u32_e32 v127, vcc, 0, v125, vcc
	v_add_co_u32_e32 v128, vcc, 0x7000, v124
	s_nop 1
	v_addc_co_u32_e32 v129, vcc, 0, v125, vcc
	global_load_dwordx4 v[124:127], v[126:127], off nt
	s_nop 0
	global_load_dwordx4 v[128:131], v[128:129], off nt
	s_branch .LBB0_822
